# N2 step: per-token all-or-nothing masks folded into QK accumulator init (sentinel bias as MFMA srcC), mask block only on partial-range steps
# speedup vs baseline: 1.0130x; 1.0054x over previous
; __device__ __forceinline__ f32x4 mfma16(bf16x8 a, bf16x8 b, f32x4 c) { return __builtin_amdgcn_mfma_f32_16x16x32_bf16(a, b, c, 0, 0, 0); }
; __device__ __forceinline__ void nsa_block_step(const bf16_t* Ks, const bf16_t* VT, const bf16x8 (&qf)[2][2], f32x4 (&O)[2][4], float (&m)[2], float (&l)[2],
;                                                int klo, int khi, int r, int q) {
;     f32x4 s[2][4];
; #pragma unroll
;     for (int x = 0; x < 2; x++)
; #pragma unroll
;         for (int kt = 0; kt < 4; kt++) s[x][kt] = (f32x4){0.f, 0.f, 0.f, 0.f};
; #pragma unroll
;     for (int kt = 0; kt < 4; kt++)
; #pragma unroll
;         for (int ks = 0; ks < 2; ks++) {
;             const bf16x8 kf = ld_frag(Ks + (kt * 16 + r) * 64 + (((ks * 4 + q) ^ (r & 7)) * 8));
; #pragma unroll
;             for (int x = 0; x < 2; x++) s[x][kt] = mfma16(kf, qf[x][ks], s[x][kt]);
;         }
;     if (!__all((klo <= 0) && (khi >= 63))) {
;         const int a = 4 * q - klo;
;         const unsigned range = (unsigned)(khi - klo);
;         const bool any = khi >= klo;
; #pragma unroll
;         for (int kt = 0; kt < 4; kt++)
; #pragma unroll
;             for (int j = 0; j < 4; j++) {
;                 const bool valid = any && ((unsigned)(kt * 16 + j + a) <= range);
; #pragma unroll
;                 for (int x = 0; x < 2; x++) s[x][kt][j] = valid ? s[x][kt][j] : -3.0e38f;
;             }
;     }
; __device__ void phaseN2_task(const Params& p, int task, char* lds, bf16_t* ydst, int ystride, volatile unsigned* uex, char* ldsb) {
;     ...
;             int klo = 0, khi = -1;
;             if (br == 0) { if ((mysel >> j) & 1u) khi = t - j * 64; }
;             else { khi = t - j * 64; klo = t - 511 - j * 64; }
;             klo = klo < 0 ? 0 : klo;
;             khi = khi > 63 ? 63 : khi;
;             nsa_block_step(Ks, VT, qf, O, m, l, klo, khi, r, q);
.LBB0_622:
	s_or_b64 exec, exec, s[10:11]
	v_lshlrev_b32_e32 v57, 6, v56
	v_sub_u32_e32 v88, v126, v57
	s_and_saveexec_b64 s[6:7], vcc
	s_xor_b64 s[6:7], exec, s[6:7]
	v_sub_u32_e32 v56, v134, v57
	v_max_i32_e32 v97, 0, v56
	s_andn2_saveexec_b64 s[6:7], s[6:7]
	v_lshrrev_b32_e32 v56, v56, v132
	v_and_b32_e32 v56, 1, v56
	v_cmp_eq_u32_e32 vcc, 1, v56
	v_mov_b32_e32 v97, 0
	s_nop 0
	v_cndmask_b32_e32 v88, -1, v88, vcc
	s_or_b64 exec, exec, s[6:7]
	v_cmp_eq_u32_e32 vcc, 0, v97
	v_cmp_lt_i32_e64 s[6:7], 62, v88
	v_cmp_lt_i32_e64 s[48:49], v88, v97
	ds_read_b128 v[56:59], v137
	ds_read_b128 v[60:63], v137 offset:2048
	s_and_b64 s[6:7], vcc, s[6:7]
	s_or_b64 s[46:47], s[6:7], s[48:49]
	s_cmp_eq_u64 s[46:47], exec
	s_cselect_b64 s[48:49], s[48:49], 0
	v_cndmask_b32_e64 v168, 0, v123, s[48:49]
	v_cndmask_b32_e64 v169, 0, v123, s[48:49]
	v_cndmask_b32_e64 v170, 0, v123, s[48:49]
	v_cndmask_b32_e64 v171, 0, v123, s[48:49]
	ds_read_b128 v[68:71], v139
	ds_read_b128 v[76:79], v139 offset:2048
	s_waitcnt lgkmcnt(3)
	v_mfma_f32_16x16x32_bf16 v[64:67], v[56:59], v[0:3], v[168:171]
	v_mfma_f32_16x16x32_bf16 v[56:59], v[56:59], v[8:11], v[168:171]
	s_waitcnt lgkmcnt(1)
	v_mfma_f32_16x16x32_bf16 v[80:83], v[68:71], v[4:7], v[64:67]
	v_mfma_f32_16x16x32_bf16 v[68:71], v[68:71], v[12:15], v[56:59]
	v_mfma_f32_16x16x32_bf16 v[56:59], v[60:63], v[0:3], v[168:171]
	v_mfma_f32_16x16x32_bf16 v[60:63], v[60:63], v[8:11], v[168:171]
	s_waitcnt lgkmcnt(0)
	v_mfma_f32_16x16x32_bf16 v[72:75], v[76:79], v[4:7], v[56:59]
	v_mfma_f32_16x16x32_bf16 v[64:67], v[76:79], v[12:15], v[60:63]
	s_nop 3
	ds_read_b128 v[56:59], v137 offset:4096
	ds_read_b128 v[76:79], v137 offset:6144
	ds_read_b128 v[104:107], v139 offset:4096
	ds_read_b128 v[108:111], v139 offset:6144
	s_waitcnt lgkmcnt(3)
	v_mfma_f32_16x16x32_bf16 v[60:63], v[56:59], v[0:3], v[168:171]
	v_mfma_f32_16x16x32_bf16 v[56:59], v[56:59], v[8:11], v[168:171]
	s_waitcnt lgkmcnt(1)
	v_mfma_f32_16x16x32_bf16 v[84:87], v[104:107], v[4:7], v[60:63]
	v_mfma_f32_16x16x32_bf16 v[60:63], v[104:107], v[12:15], v[56:59]
	v_mfma_f32_16x16x32_bf16 v[56:59], v[76:79], v[0:3], v[168:171]
	v_mfma_f32_16x16x32_bf16 v[104:107], v[76:79], v[8:11], v[168:171]
	s_waitcnt lgkmcnt(0)
	v_mfma_f32_16x16x32_bf16 v[76:79], v[108:111], v[4:7], v[56:59]
	v_mfma_f32_16x16x32_bf16 v[56:59], v[108:111], v[12:15], v[104:107]
	s_cmp_eq_u64 s[46:47], exec
	s_cbranch_scc1 .LBB0_628
	v_min_i32_e32 v88, 63, v88
	v_sub_u32_e32 v104, v88, v97
	v_cmp_ge_i32_e32 vcc, v88, v97
	v_sub_u32_e32 v88, v129, v97
	v_cmp_le_u32_e64 s[6:7], v88, v104
	s_and_b64 s[6:7], vcc, s[6:7]
	v_add_u32_e32 v97, 1, v88
	v_cndmask_b32_e64 v80, v123, v80, s[6:7]
	v_cndmask_b32_e64 v68, v123, v68, s[6:7]
	v_cmp_le_u32_e64 s[6:7], v97, v104
	s_and_b64 s[6:7], vcc, s[6:7]
	v_add_u32_e32 v97, 2, v88
	v_cndmask_b32_e64 v81, v123, v81, s[6:7]
	v_cndmask_b32_e64 v69, v123, v69, s[6:7]
	v_cmp_le_u32_e64 s[6:7], v97, v104
	s_and_b64 s[6:7], vcc, s[6:7]
	v_add_u32_e32 v97, 3, v88
	v_cndmask_b32_e64 v82, v123, v82, s[6:7]
	v_cndmask_b32_e64 v70, v123, v70, s[6:7]
	v_cmp_le_u32_e64 s[6:7], v97, v104
	s_and_b64 s[6:7], vcc, s[6:7]
	v_add_u32_e32 v97, 16, v88
	v_cndmask_b32_e64 v83, v123, v83, s[6:7]
	v_cndmask_b32_e64 v71, v123, v71, s[6:7]
	v_cmp_le_u32_e64 s[6:7], v97, v104
	s_and_b64 s[6:7], vcc, s[6:7]
	v_add_u32_e32 v97, 17, v88
	v_cndmask_b32_e64 v72, v123, v72, s[6:7]
	v_cndmask_b32_e64 v64, v123, v64, s[6:7]
	v_cmp_le_u32_e64 s[6:7], v97, v104
	s_and_b64 s[6:7], vcc, s[6:7]
	v_add_u32_e32 v97, 18, v88
	v_cndmask_b32_e64 v73, v123, v73, s[6:7]
	v_cndmask_b32_e64 v65, v123, v65, s[6:7]
	v_cmp_le_u32_e64 s[6:7], v97, v104
	s_and_b64 s[6:7], vcc, s[6:7]
	v_add_u32_e32 v97, 19, v88
	v_cndmask_b32_e64 v74, v123, v74, s[6:7]
	v_cndmask_b32_e64 v66, v123, v66, s[6:7]
	v_cmp_le_u32_e64 s[6:7], v97, v104
	s_and_b64 s[6:7], vcc, s[6:7]
	v_add_u32_e32 v97, 32, v88
	v_cndmask_b32_e64 v75, v123, v75, s[6:7]
	v_cndmask_b32_e64 v67, v123, v67, s[6:7]
	v_cmp_le_u32_e64 s[6:7], v97, v104
	s_and_b64 s[6:7], vcc, s[6:7]
	v_add_u32_e32 v97, 33, v88
	v_cndmask_b32_e64 v84, v123, v84, s[6:7]
	v_cndmask_b32_e64 v60, v123, v60, s[6:7]
	v_cmp_le_u32_e64 s[6:7], v97, v104
	s_and_b64 s[6:7], vcc, s[6:7]
	v_add_u32_e32 v97, 34, v88
	v_cndmask_b32_e64 v85, v123, v85, s[6:7]
	v_cndmask_b32_e64 v61, v123, v61, s[6:7]
	v_cmp_le_u32_e64 s[6:7], v97, v104
	s_and_b64 s[6:7], vcc, s[6:7]
	v_add_u32_e32 v97, 35, v88
	v_cndmask_b32_e64 v86, v123, v86, s[6:7]
	v_cndmask_b32_e64 v62, v123, v62, s[6:7]
	v_cmp_le_u32_e64 s[6:7], v97, v104
	s_and_b64 s[6:7], vcc, s[6:7]
	v_add_u32_e32 v97, 48, v88
	v_cndmask_b32_e64 v87, v123, v87, s[6:7]
	v_cndmask_b32_e64 v63, v123, v63, s[6:7]
	v_cmp_le_u32_e64 s[6:7], v97, v104
	s_and_b64 s[6:7], vcc, s[6:7]
	v_add_u32_e32 v97, 49, v88
	v_cndmask_b32_e64 v76, v123, v76, s[6:7]
	v_cndmask_b32_e64 v56, v123, v56, s[6:7]
	v_cmp_le_u32_e64 s[6:7], v97, v104
	s_and_b64 s[6:7], vcc, s[6:7]
	v_add_u32_e32 v97, 50, v88
	v_cndmask_b32_e64 v77, v123, v77, s[6:7]
	v_cndmask_b32_e64 v57, v123, v57, s[6:7]
	v_cmp_le_u32_e64 s[6:7], v97, v104
	s_and_b64 s[6:7], vcc, s[6:7]
	v_add_u32_e32 v88, 51, v88
	v_cndmask_b32_e64 v78, v123, v78, s[6:7]
	v_cndmask_b32_e64 v58, v123, v58, s[6:7]
	v_cmp_le_u32_e64 s[6:7], v88, v104
	s_and_b64 vcc, vcc, s[6:7]
	v_cndmask_b32_e32 v79, v123, v79, vcc
	v_cndmask_b32_e32 v59, v123, v59, vcc
